# prompt attention: straight-line softmax for K tiles with uniform (clamped) position bias - max over raw scores, folded fma+exp2 in place, packed f32 sums
# speedup vs baseline: 1.0155x; 1.0068x over previous
.LBB0_1429:
	v_mov_b32_e32 v4, v252
	s_waitcnt vmcnt(63) expcnt(7) lgkmcnt(15)
	v_readfirstlane_b32 s4, v4
	s_barrier
	s_load_dwordx2 s[2:3], s[0:1], 0x40
	s_ashr_i32 s10, s4, 6
	v_and_b32_e32 v173, 63, v4
	s_mul_i32 s6, s10, 0x101
	s_mul_i32 s5, s10, 0x410
	v_add_u32_e32 v2, s6, v173
	s_add_i32 s8, s5, 0
	v_ashrrev_i32_e32 v3, 31, v2
	v_or_b32_e32 v0, 0xffffffc0, v173
	v_lshl_add_u32 v5, v173, 2, s8
	s_waitcnt lgkmcnt(0)
	v_lshl_add_u64 v[2:3], v[2:3], 2, s[2:3]
	s_mov_b64 s[2:3], 0
	global_load_dword v243, v[2:3], off
	global_load_dword v248, v[2:3], off offset:256
	global_load_dword v249, v[2:3], off offset:512
	global_load_dword v250, v[2:3], off offset:768
	v_cmp_eq_u32_e32 vcc, 0xffffffc0, v0
	s_and_saveexec_b64 s[2:3], vcc
	global_load_dword v251, v[2:3], off offset:1024
	s_waitcnt vmcnt(0)
	v_mul_f32_e32 v251, 0x3fb8aa3b, v251
	ds_write_b32 v5, v251 offset:1024
	s_or_b64 exec, exec, s[2:3]
	v_mul_f32_e32 v243, 0x3fb8aa3b, v243
	v_mul_f32_e32 v248, 0x3fb8aa3b, v248
	v_mul_f32_e32 v249, 0x3fb8aa3b, v249
	v_mul_f32_e32 v250, 0x3fb8aa3b, v250
	ds_write_b32 v5, v243
	ds_write_b32 v5, v248 offset:256
	ds_write_b32 v5, v249 offset:512
	ds_write_b32 v5, v250 offset:768
	s_add_i32 s11, s18, 0xffb9
	s_and_b32 s9, s11, 0xffff
	s_mul_i32 s2, s9, 0x8889
	s_lshr_b32 s2, s2, 22
	s_lshl_b32 s3, s2, 7
	s_mulk_i32 s2, 0x78
	s_sub_i32 s2, s11, s2
	s_add_i32 s2, s2, 8
	s_and_b32 s2, s2, 0xffff
	s_add_i32 s33, s3, s2
	s_lshr_b32 s2, s33, 7
	s_lshl_b32 s76, s2, 22
	s_lshl_b32 s2, s2, 3
	s_and_b32 s6, s4, 0xffffffc0
	s_add_i32 s2, s10, s2
	s_ashr_i32 s7, s6, 31
	s_ashr_i32 s3, s2, 31
	s_lshl_b64 s[2:3], s[2:3], 20
	s_lshl_b64 s[4:5], s[6:7], 1
	v_lshrrev_b32_e32 v5, 5, v173
	s_add_u32 s30, s95, s4
	v_and_b32_e32 v172, 31, v4
	s_addc_u32 s31, s22, s5
	v_lshlrev_b32_e32 v0, 4, v5
	v_lshl_add_u64 v[2:3], s[30:31], 0, v[0:1]
	v_lshl_or_b32 v0, s33, 6, v172
	v_lshlrev_b64 v[6:7], 10, v[0:1]
	v_or_b32_e32 v162, 32, v0
	v_mov_b32_e32 v163, v1
	v_lshl_add_u64 v[18:19], v[2:3], 0, v[6:7]
	v_lshlrev_b64 v[6:7], 10, v[162:163]
	s_waitcnt lgkmcnt(0)
	s_barrier
	v_lshl_add_u64 v[2:3], v[2:3], 0, v[6:7]
	global_load_dwordx4 v[6:9], v[18:19], off
	global_load_dwordx4 v[10:13], v[18:19], off offset:32
	global_load_dwordx4 v[14:17], v[18:19], off offset:64
	s_nop 0
	global_load_dwordx4 v[18:21], v[18:19], off offset:96
	s_nop 0
	global_load_dwordx4 v[22:25], v[2:3], off
	global_load_dwordx4 v[26:29], v[2:3], off offset:32
	global_load_dwordx4 v[30:33], v[2:3], off offset:64
	global_load_dwordx4 v[34:37], v[2:3], off offset:96
	s_mulk_i32 s10, 0x1bf0
	v_lshlrev_b32_e32 v38, 4, v173
	s_add_i32 s10, s8, s10
	v_and_b32_e32 v3, 32, v4
	v_add_u32_e32 v174, s10, v38
	s_lshl_b32 s10, s11, 16
	v_lshlrev_b32_e32 v2, 10, v172
	v_lshrrev_b32_e32 v3, 1, v3
	v_or3_b32 v2, s10, v2, v3
	s_lshl_b64 s[10:11], s[76:77], 1
	s_add_u32 s10, s10, s4
	v_mov_b32_e32 v3, v1
	s_addc_u32 s11, s11, s5
	v_lshl_add_u64 v[2:3], s[10:11], 0, v[2:3]
	s_mul_hi_u32 s10, s9, 0x2222223
	s_mul_hi_u32 s11, s10, 0x780000
	s_mul_i32 s30, s10, 0x780000
	v_subrev_co_u32_e32 v166, vcc, s30, v2
	v_mov_b32_e32 v2, s11
	s_lshl_b32 s9, s9, 13
	v_subb_co_u32_e32 v167, vcc, v3, v2, vcc
	s_add_u32 s2, s2, s9
	v_lshlrev_b32_e32 v2, 4, v172
	v_lshlrev_b32_e32 v3, 10, v5
	v_or3_b32 v2, v3, v2, s2
	s_addc_u32 s3, s3, 0
	v_or_b32_e32 v3, 0x200, v2
	s_mul_i32 s10, s10, 0xf0000
	v_mov_b32_e32 v4, s3
	v_subrev_co_u32_e32 v168, vcc, s10, v3
	v_lshlrev_b32_e32 v165, 2, v5
	s_nop 0
	v_subbrev_co_u32_e32 v169, vcc, 0, v4, vcc
	v_subrev_co_u32_e32 v170, vcc, s10, v2
	v_sub_u32_e32 v2, v172, v165
	s_nop 0
	v_subbrev_co_u32_e32 v171, vcc, 0, v4, vcc
	v_add_u32_e32 v177, 0x220, v2
	v_mov_b32_e32 v2, v1
	v_mov_b32_e32 v3, v1
	v_mov_b32_e32 v4, v1
	v_mov_b32_e32 v5, v1
	v_mov_b32_e32 v175, 0
	v_mov_b32_e32 v189, 0xf149f2ca
	s_mov_b32 s9, -1
	v_mov_b32_e32 v199, 0xf149f2ca
	v_mov_b32_e32 v176, 0
	v_readfirstlane_b32 s98, v252
	v_mbcnt_lo_u32_b32 v249, -1, 0
	v_mbcnt_hi_u32_b32 v249, -1, v249
	s_lshr_b32 s101, s98, 6
	s_lshl_b32 s98, s101, 13
	s_add_i32 s98, s98, 0x14000
	s_add_i32 s99, s98, 0x1c00
	s_mov_b32 s100, 0x1000
	s_cmp_eq_u32 s101, 7
	s_cselect_b32 s99, 0x3000, s99
	s_cselect_b32 s100, 0xfffe0400, s100
	v_and_b32_e32 v246, 31, v249
	v_lshrrev_b32_e32 v247, 5, v249
	v_bfe_u32 v248, v249, 1, 3
	v_lshl_add_u32 v250, v246, 7, s98
	v_xor_b32_e32 v241, v247, v248
	v_lshl_add_u32 v241, v241, 4, v250
	v_or_b32_e32 v242, 2, v247
	v_xor_b32_e32 v242, v242, v248
	v_lshl_add_u32 v242, v242, 4, v250
	v_or_b32_e32 v243, 4, v247
	v_xor_b32_e32 v243, v243, v248
	v_lshl_add_u32 v243, v243, 4, v250
	v_or_b32_e32 v244, 6, v247
	v_xor_b32_e32 v244, v244, v248
	v_lshl_add_u32 v244, v244, 4, v250
	v_mov_b32_e32 v245, 0x1000
	v_mov_b32_e32 v251, s100
	v_cmp_lt_u32_e32 vcc, 23, v246
	s_nop 1
	v_cndmask_b32_e32 v245, v245, v251, vcc
	v_add_u32_e32 v248, v244, v245
	v_add_u32_e32 v247, v243, v245
	v_add_u32_e32 v246, v242, v245
	v_add_u32_e32 v245, v241, v245
	v_lshrrev_b32_e32 v250, 3, v249
	v_lshlrev_b32_e32 v250, 10, v250
	v_and_b32_e32 v251, 7, v249
	v_lshrrev_b32_e32 v142, 4, v249
	v_xor_b32_e32 v251, v251, v142
	v_lshl_add_u32 v142, v251, 4, v250
	v_xor_b32_e32 v251, 4, v251
	v_lshl_add_u32 v250, v251, 4, v250
	v_add_u32_e32 v250, 0x2000, v250
	v_readfirstlane_b32 s100, v166
	v_readfirstlane_b32 s101, v167
	s_nop 0
	s_add_u32 s100, s100, s86
	s_addc_u32 s101, s101, s87
	s_add_u32 s100, s100, 0x85ee200
	s_addc_u32 s101, s101, 0
	v_mov_b32_e32 v143, 0
	v_mov_b32_e32 v251, 0
	v_lshl_add_u64 v[166:167], s[100:101], 0, v[142:143]
	v_lshl_add_u64 v[250:251], s[100:101], 0, v[250:251]
	s_mov_b64 s[100:101], 0x4000
	s_mov_b32 m0, s98
	s_nop 0
	global_load_lds_dwordx4 v[166:167], off
	s_add_i32 m0, s98, 0x400
	s_nop 0
	global_load_lds_dwordx4 v[250:251], off
	v_lshl_add_u64 v[142:143], v[166:167], 0, s[100:101]
	s_add_i32 m0, s98, 0x800
	s_nop 0
	global_load_lds_dwordx4 v[142:143], off
	v_lshl_add_u64 v[144:145], v[250:251], 0, s[100:101]
	s_add_i32 m0, s98, 0xc00
	s_nop 0
	global_load_lds_dwordx4 v[144:145], off
	v_lshl_add_u64 v[142:143], v[142:143], 0, s[100:101]
	s_add_i32 m0, s98, 0x1000
	s_nop 0
	global_load_lds_dwordx4 v[142:143], off
	v_lshl_add_u64 v[144:145], v[144:145], 0, s[100:101]
	s_add_i32 m0, s98, 0x1400
	s_nop 0
	global_load_lds_dwordx4 v[144:145], off
	v_lshl_add_u64 v[142:143], v[142:143], 0, s[100:101]
	s_add_i32 m0, s98, 0x1800
	s_nop 0
	global_load_lds_dwordx4 v[142:143], off
	v_lshl_add_u64 v[144:145], v[144:145], 0, s[100:101]
	s_mov_b32 m0, s99
	s_nop 0
	global_load_lds_dwordx4 v[144:145], off
	s_waitcnt vmcnt(7)
	s_waitcnt vmcnt(6)
	s_waitcnt vmcnt(5)
	s_waitcnt vmcnt(4)
	s_waitcnt vmcnt(3)
	s_waitcnt vmcnt(2)
	s_waitcnt vmcnt(1)
	s_waitcnt vmcnt(0)
	ds_write_b128 v174, v[6:9] offset:16384
	ds_write_b128 v174, v[10:13] offset:17408
	ds_write_b128 v174, v[14:17] offset:18432
	ds_write_b128 v174, v[18:21] offset:19456
	ds_write_b128 v174, v[22:25] offset:20480
	ds_write_b128 v174, v[26:29] offset:21504
	ds_write_b128 v174, v[30:33] offset:22528
	ds_write_b128 v174, v[34:37] offset:23552
	v_mov_b32_e32 v16, v1
	v_mov_b32_e32 v17, v1
	v_mov_b32_e32 v6, v1
	v_mov_b32_e32 v7, v1
	v_mov_b32_e32 v8, v1
	v_mov_b32_e32 v9, v1
	v_mov_b32_e32 v10, v1
	v_mov_b32_e32 v11, v1
	v_mov_b32_e32 v12, v1
	v_mov_b32_e32 v13, v1
	v_mov_b32_e32 v14, v1
	v_mov_b32_e32 v15, v1
	v_mov_b64_e32 v[48:49], v[16:17]
	v_mov_b64_e32 v[32:33], v[16:17]
	v_mov_b64_e32 v[64:65], v[16:17]
	v_mov_b64_e32 v[46:47], v[14:15]
	v_mov_b64_e32 v[44:45], v[12:13]
	v_mov_b64_e32 v[42:43], v[10:11]
	v_mov_b64_e32 v[40:41], v[8:9]
	v_mov_b64_e32 v[38:39], v[6:7]
	v_mov_b64_e32 v[36:37], v[4:5]
	v_mov_b64_e32 v[34:35], v[2:3]
	v_mov_b64_e32 v[30:31], v[14:15]
	v_mov_b64_e32 v[28:29], v[12:13]
	v_mov_b64_e32 v[26:27], v[10:11]
	v_mov_b64_e32 v[24:25], v[8:9]
	v_mov_b64_e32 v[22:23], v[6:7]
	v_mov_b64_e32 v[20:21], v[4:5]
	v_mov_b64_e32 v[18:19], v[2:3]
	v_mov_b64_e32 v[62:63], v[14:15]
	v_mov_b64_e32 v[60:61], v[12:13]
	v_mov_b64_e32 v[58:59], v[10:11]
	v_mov_b64_e32 v[56:57], v[8:9]
	v_mov_b64_e32 v[54:55], v[6:7]
	v_mov_b64_e32 v[52:53], v[4:5]
	v_mov_b64_e32 v[50:51], v[2:3]
	v_mov_b32_e32 v249, 0x3e38aa3b

.Lattn_nopf:
	v_lshl_add_u64 v[130:131], s[86:87], 0, v[170:171]
	v_add_co_u32_e32 v132, vcc, s88, v130
	s_nop 1
	v_addc_co_u32_e32 v133, vcc, 0, v131, vcc
	v_add_co_u32_e32 v130, vcc, s17, v130
	global_load_dwordx4 v[158:161], v[132:133], off offset:512
	global_load_dwordx4 v[154:157], v[132:133], off offset:1024
	global_load_dwordx4 v[150:153], v[132:133], off offset:2560
	global_load_dwordx4 v[146:149], v[132:133], off offset:3072
	v_addc_co_u32_e32 v131, vcc, 0, v131, vcc
	v_lshl_add_u64 v[132:133], s[86:87], 0, v[168:169]
	v_add_co_u32_e32 v132, vcc, 0xae6f000, v132
	s_nop 1
	v_addc_co_u32_e32 v133, vcc, 0, v133, vcc
	global_load_dwordx4 v[138:141], v[130:131], off offset:512
	global_load_dwordx4 v[134:137], v[130:131], off offset:2560
	global_load_dwordx4 v[142:145], v[132:133], off offset:512
	s_nop 0
	global_load_dwordx4 v[130:133], v[132:133], off offset:2560
	v_mov_b32_e32 v188, s8
	ds_read_b32 v190, v188 offset:1024
	s_cmp_lt_u32 s9, 6
	s_cbranch_scc1 .Lattn_near_p
	s_cmp_gt_u32 s9, 5
	v_subrev_u32_e32 v188, 32, v177
	s_cselect_b64 s[2:3], -1, 0
	s_cmp_lt_u32 s9, 6
	v_min_i32_e32 v191, 0x80, v188
	s_waitcnt lgkmcnt(0)
	v_mov_b32_e32 v201, v190
	s_cbranch_scc1 .LBB0_1434
	v_lshl_add_u32 v188, v191, 2, s8
	ds_read_b32 v201, v188 offset:512

.Lattn_near_p:
	v_subrev_u32_e32 v188, 64, v177
	v_xor_b32_e32 v232, 32, v179
	v_lshlrev_b32_e32 v232, 2, v232
	v_max3_f32 v231, v98, v99, v100
	v_max3_f32 v231, v231, v101, v102
	v_max3_f32 v231, v231, v103, v104
	v_max3_f32 v231, v231, v105, v106
	v_max3_f32 v231, v231, v107, v108
	v_max3_f32 v231, v231, v109, v110
	v_max3_f32 v231, v231, v111, v112
	v_max3_f32 v231, v231, v113, v114
	v_max3_f32 v231, v231, v115, v116
	v_max3_f32 v231, v231, v117, v118
	v_max3_f32 v231, v231, v119, v120
	v_max3_f32 v231, v231, v121, v122
	v_max3_f32 v231, v231, v123, v124
	v_max3_f32 v231, v231, v125, v126
	v_max3_f32 v231, v231, v127, v128
	v_max_f32_e32 v231, v231, v129
	s_waitcnt lgkmcnt(0)
	v_fma_f32 v231, v231, v249, v190
	ds_bpermute_b32 v233, v232, v231
	v_max3_f32 v234, v66, v67, v68
	v_max3_f32 v234, v234, v69, v70
	v_max3_f32 v234, v234, v71, v72
	v_max3_f32 v234, v234, v73, v74
	v_max3_f32 v234, v234, v75, v76
	v_max3_f32 v234, v234, v77, v78
	v_max3_f32 v234, v234, v79, v80
	v_max3_f32 v234, v234, v81, v82
	v_max3_f32 v234, v234, v83, v84
	v_max3_f32 v234, v234, v85, v86
	v_max3_f32 v234, v234, v87, v88
	v_max3_f32 v234, v234, v89, v90
	v_max3_f32 v234, v234, v91, v92
	v_max3_f32 v234, v234, v93, v94
	v_max3_f32 v234, v234, v95, v96
	v_max_f32_e32 v234, v234, v97
	v_fma_f32 v234, v234, v249, v190
	ds_bpermute_b32 v235, v232, v234
	s_waitcnt lgkmcnt(1)
	v_max3_f32 v236, v199, v231, v233
	v_sub_f32_e32 v226, v199, v236
	v_sub_f32_e32 v238, v190, v236
	v_exp_f32_e32 v226, v226
	v_pk_fma_f32 v[98:99], v[98:99], v[248:249], v[238:239] op_sel:[0,1,0] op_sel_hi:[1,1,0]
	v_pk_fma_f32 v[100:101], v[100:101], v[248:249], v[238:239] op_sel:[0,1,0] op_sel_hi:[1,1,0]
	v_pk_fma_f32 v[102:103], v[102:103], v[248:249], v[238:239] op_sel:[0,1,0] op_sel_hi:[1,1,0]
	v_pk_fma_f32 v[104:105], v[104:105], v[248:249], v[238:239] op_sel:[0,1,0] op_sel_hi:[1,1,0]
	v_pk_fma_f32 v[106:107], v[106:107], v[248:249], v[238:239] op_sel:[0,1,0] op_sel_hi:[1,1,0]
	v_pk_fma_f32 v[108:109], v[108:109], v[248:249], v[238:239] op_sel:[0,1,0] op_sel_hi:[1,1,0]
	v_pk_fma_f32 v[110:111], v[110:111], v[248:249], v[238:239] op_sel:[0,1,0] op_sel_hi:[1,1,0]
	v_pk_fma_f32 v[112:113], v[112:113], v[248:249], v[238:239] op_sel:[0,1,0] op_sel_hi:[1,1,0]
	v_pk_fma_f32 v[114:115], v[114:115], v[248:249], v[238:239] op_sel:[0,1,0] op_sel_hi:[1,1,0]
	v_pk_fma_f32 v[116:117], v[116:117], v[248:249], v[238:239] op_sel:[0,1,0] op_sel_hi:[1,1,0]
	v_pk_fma_f32 v[118:119], v[118:119], v[248:249], v[238:239] op_sel:[0,1,0] op_sel_hi:[1,1,0]
	v_pk_fma_f32 v[120:121], v[120:121], v[248:249], v[238:239] op_sel:[0,1,0] op_sel_hi:[1,1,0]
	v_pk_fma_f32 v[122:123], v[122:123], v[248:249], v[238:239] op_sel:[0,1,0] op_sel_hi:[1,1,0]
	v_pk_fma_f32 v[124:125], v[124:125], v[248:249], v[238:239] op_sel:[0,1,0] op_sel_hi:[1,1,0]
	v_pk_fma_f32 v[126:127], v[126:127], v[248:249], v[238:239] op_sel:[0,1,0] op_sel_hi:[1,1,0]
	v_pk_fma_f32 v[128:129], v[128:129], v[248:249], v[238:239] op_sel:[0,1,0] op_sel_hi:[1,1,0]
	v_exp_f32_e32 v98, v98
	v_exp_f32_e32 v99, v99
	v_exp_f32_e32 v100, v100
	v_exp_f32_e32 v101, v101
	v_exp_f32_e32 v102, v102
	v_exp_f32_e32 v103, v103
	v_exp_f32_e32 v104, v104
	v_exp_f32_e32 v105, v105
	v_exp_f32_e32 v106, v106
	v_exp_f32_e32 v107, v107
	v_exp_f32_e32 v108, v108
	v_exp_f32_e32 v109, v109
	v_exp_f32_e32 v110, v110
	v_exp_f32_e32 v111, v111
	v_exp_f32_e32 v112, v112
	v_exp_f32_e32 v113, v113
	v_exp_f32_e32 v114, v114
	v_exp_f32_e32 v115, v115
	v_exp_f32_e32 v116, v116
	v_exp_f32_e32 v117, v117
	v_exp_f32_e32 v118, v118
	v_exp_f32_e32 v119, v119
	v_exp_f32_e32 v120, v120
	v_exp_f32_e32 v121, v121
	v_exp_f32_e32 v122, v122
	v_exp_f32_e32 v123, v123
	v_exp_f32_e32 v124, v124
	v_exp_f32_e32 v125, v125
	v_exp_f32_e32 v126, v126
	v_exp_f32_e32 v127, v127
	v_exp_f32_e32 v128, v128
	v_exp_f32_e32 v129, v129
	s_waitcnt lgkmcnt(0)
	v_max3_f32 v218, v189, v234, v235
	v_sub_f32_e32 v228, v189, v218
	v_sub_f32_e32 v240, v190, v218
	v_exp_f32_e32 v228, v228
	v_pk_fma_f32 v[66:67], v[66:67], v[248:249], v[240:241] op_sel:[0,1,0] op_sel_hi:[1,1,0]
	v_pk_fma_f32 v[68:69], v[68:69], v[248:249], v[240:241] op_sel:[0,1,0] op_sel_hi:[1,1,0]
	v_pk_fma_f32 v[70:71], v[70:71], v[248:249], v[240:241] op_sel:[0,1,0] op_sel_hi:[1,1,0]
	v_pk_fma_f32 v[72:73], v[72:73], v[248:249], v[240:241] op_sel:[0,1,0] op_sel_hi:[1,1,0]
	v_pk_fma_f32 v[74:75], v[74:75], v[248:249], v[240:241] op_sel:[0,1,0] op_sel_hi:[1,1,0]
	v_pk_fma_f32 v[76:77], v[76:77], v[248:249], v[240:241] op_sel:[0,1,0] op_sel_hi:[1,1,0]
	v_pk_fma_f32 v[78:79], v[78:79], v[248:249], v[240:241] op_sel:[0,1,0] op_sel_hi:[1,1,0]
	v_pk_fma_f32 v[80:81], v[80:81], v[248:249], v[240:241] op_sel:[0,1,0] op_sel_hi:[1,1,0]
	v_pk_fma_f32 v[82:83], v[82:83], v[248:249], v[240:241] op_sel:[0,1,0] op_sel_hi:[1,1,0]
	v_pk_fma_f32 v[84:85], v[84:85], v[248:249], v[240:241] op_sel:[0,1,0] op_sel_hi:[1,1,0]
	v_pk_fma_f32 v[86:87], v[86:87], v[248:249], v[240:241] op_sel:[0,1,0] op_sel_hi:[1,1,0]
	v_pk_fma_f32 v[88:89], v[88:89], v[248:249], v[240:241] op_sel:[0,1,0] op_sel_hi:[1,1,0]
	v_pk_fma_f32 v[90:91], v[90:91], v[248:249], v[240:241] op_sel:[0,1,0] op_sel_hi:[1,1,0]
	v_pk_fma_f32 v[92:93], v[92:93], v[248:249], v[240:241] op_sel:[0,1,0] op_sel_hi:[1,1,0]
	v_pk_fma_f32 v[94:95], v[94:95], v[248:249], v[240:241] op_sel:[0,1,0] op_sel_hi:[1,1,0]
	v_pk_fma_f32 v[96:97], v[96:97], v[248:249], v[240:241] op_sel:[0,1,0] op_sel_hi:[1,1,0]
	v_exp_f32_e32 v66, v66
	v_exp_f32_e32 v67, v67
	v_exp_f32_e32 v68, v68
	v_exp_f32_e32 v69, v69
	v_exp_f32_e32 v70, v70
	v_exp_f32_e32 v71, v71
	v_exp_f32_e32 v72, v72
	v_exp_f32_e32 v73, v73
	v_exp_f32_e32 v74, v74
	v_exp_f32_e32 v75, v75
	v_exp_f32_e32 v76, v76
	v_exp_f32_e32 v77, v77
	v_exp_f32_e32 v78, v78
	v_exp_f32_e32 v79, v79
	v_exp_f32_e32 v80, v80
	v_exp_f32_e32 v81, v81
	v_exp_f32_e32 v82, v82
	v_exp_f32_e32 v83, v83
	v_exp_f32_e32 v84, v84
	v_exp_f32_e32 v85, v85
	v_exp_f32_e32 v86, v86
	v_exp_f32_e32 v87, v87
	v_exp_f32_e32 v88, v88
	v_exp_f32_e32 v89, v89
	v_exp_f32_e32 v90, v90
	v_exp_f32_e32 v91, v91
	v_exp_f32_e32 v92, v92
	v_exp_f32_e32 v93, v93
	v_exp_f32_e32 v94, v94
	v_exp_f32_e32 v95, v95
	v_exp_f32_e32 v96, v96
	v_exp_f32_e32 v97, v97
	v_pk_add_f32 v[212:213], v[98:99], v[100:101]
	v_pk_add_f32 v[214:215], v[102:103], v[104:105]
	v_pk_add_f32 v[212:213], v[212:213], v[106:107]
	v_pk_add_f32 v[214:215], v[214:215], v[108:109]
	v_pk_add_f32 v[212:213], v[212:213], v[110:111]
	v_pk_add_f32 v[214:215], v[214:215], v[112:113]
	v_pk_add_f32 v[212:213], v[212:213], v[114:115]
	v_pk_add_f32 v[214:215], v[214:215], v[116:117]
	v_pk_add_f32 v[212:213], v[212:213], v[118:119]
	v_pk_add_f32 v[214:215], v[214:215], v[120:121]
	v_pk_add_f32 v[212:213], v[212:213], v[122:123]
	v_pk_add_f32 v[214:215], v[214:215], v[124:125]
	v_pk_add_f32 v[212:213], v[212:213], v[126:127]
	v_pk_add_f32 v[214:215], v[214:215], v[128:129]
	v_pk_add_f32 v[212:213], v[212:213], v[214:215]
	v_add_f32_e32 v210, v212, v213
	ds_bpermute_b32 v211, v232, v210
	v_pk_add_f32 v[220:221], v[66:67], v[68:69]
	v_pk_add_f32 v[222:223], v[70:71], v[72:73]
	v_pk_add_f32 v[220:221], v[220:221], v[74:75]
	v_pk_add_f32 v[222:223], v[222:223], v[76:77]
	v_pk_add_f32 v[220:221], v[220:221], v[78:79]
	v_pk_add_f32 v[222:223], v[222:223], v[80:81]
	v_pk_add_f32 v[220:221], v[220:221], v[82:83]
	v_pk_add_f32 v[222:223], v[222:223], v[84:85]
	v_pk_add_f32 v[220:221], v[220:221], v[86:87]
	v_pk_add_f32 v[222:223], v[222:223], v[88:89]
	v_pk_add_f32 v[220:221], v[220:221], v[90:91]
	v_pk_add_f32 v[222:223], v[222:223], v[92:93]
	v_pk_add_f32 v[220:221], v[220:221], v[94:95]
	v_pk_add_f32 v[222:223], v[222:223], v[96:97]
	v_pk_add_f32 v[220:221], v[220:221], v[222:223]
	v_add_f32_e32 v224, v220, v221
	ds_bpermute_b32 v225, v232, v224
	v_cmp_neq_f32_e32 vcc, 1.0, v226
	s_cbranch_vccz .Lattn_near_p_sa
	v_pk_mul_f32 v[64:65], v[64:65], v[226:227] op_sel_hi:[1,0]
	v_pk_mul_f32 v[62:63], v[62:63], v[226:227] op_sel_hi:[1,0]
	v_pk_mul_f32 v[60:61], v[60:61], v[226:227] op_sel_hi:[1,0]
	v_pk_mul_f32 v[58:59], v[58:59], v[226:227] op_sel_hi:[1,0]
	v_pk_mul_f32 v[56:57], v[56:57], v[226:227] op_sel_hi:[1,0]
	v_pk_mul_f32 v[54:55], v[54:55], v[226:227] op_sel_hi:[1,0]
	v_pk_mul_f32 v[52:53], v[52:53], v[226:227] op_sel_hi:[1,0]
	v_pk_mul_f32 v[50:51], v[50:51], v[226:227] op_sel_hi:[1,0]
	v_pk_mul_f32 v[48:49], v[48:49], v[226:227] op_sel_hi:[1,0]
	v_pk_mul_f32 v[46:47], v[46:47], v[226:227] op_sel_hi:[1,0]
	v_pk_mul_f32 v[44:45], v[44:45], v[226:227] op_sel_hi:[1,0]
	v_pk_mul_f32 v[42:43], v[42:43], v[226:227] op_sel_hi:[1,0]
	v_pk_mul_f32 v[40:41], v[40:41], v[226:227] op_sel_hi:[1,0]
	v_pk_mul_f32 v[38:39], v[38:39], v[226:227] op_sel_hi:[1,0]
	v_pk_mul_f32 v[36:37], v[36:37], v[226:227] op_sel_hi:[1,0]
	v_pk_mul_f32 v[34:35], v[34:35], v[226:227] op_sel_hi:[1,0]
.Lattn_near_p_sa:
	v_cmp_neq_f32_e32 vcc, 1.0, v228
	s_cbranch_vccz .Lattn_near_p_sb
	v_pk_mul_f32 v[32:33], v[32:33], v[228:229] op_sel_hi:[1,0]
	v_pk_mul_f32 v[30:31], v[30:31], v[228:229] op_sel_hi:[1,0]
	v_pk_mul_f32 v[28:29], v[28:29], v[228:229] op_sel_hi:[1,0]
	v_pk_mul_f32 v[26:27], v[26:27], v[228:229] op_sel_hi:[1,0]
	v_pk_mul_f32 v[24:25], v[24:25], v[228:229] op_sel_hi:[1,0]
	v_pk_mul_f32 v[22:23], v[22:23], v[228:229] op_sel_hi:[1,0]
	v_pk_mul_f32 v[20:21], v[20:21], v[228:229] op_sel_hi:[1,0]
	v_pk_mul_f32 v[18:19], v[18:19], v[228:229] op_sel_hi:[1,0]
	v_pk_mul_f32 v[16:17], v[16:17], v[228:229] op_sel_hi:[1,0]
	v_pk_mul_f32 v[14:15], v[14:15], v[228:229] op_sel_hi:[1,0]
	v_pk_mul_f32 v[12:13], v[12:13], v[228:229] op_sel_hi:[1,0]
	v_pk_mul_f32 v[10:11], v[10:11], v[228:229] op_sel_hi:[1,0]
	v_pk_mul_f32 v[8:9], v[8:9], v[228:229] op_sel_hi:[1,0]
	v_pk_mul_f32 v[6:7], v[6:7], v[228:229] op_sel_hi:[1,0]
	v_pk_mul_f32 v[4:5], v[4:5], v[228:229] op_sel_hi:[1,0]
	v_pk_mul_f32 v[2:3], v[2:3], v[228:229] op_sel_hi:[1,0]
.Lattn_near_p_sb:
	v_cvt_pk_bf16_f32 v98, v98, v99
	v_cvt_pk_bf16_f32 v99, v100, v101
	v_cvt_pk_bf16_f32 v100, v102, v103
	v_cvt_pk_bf16_f32 v101, v104, v105
	v_cvt_pk_bf16_f32 v66, v66, v67
	v_cvt_pk_bf16_f32 v67, v68, v69
	v_cvt_pk_bf16_f32 v68, v70, v71
	v_cvt_pk_bf16_f32 v69, v72, v73
	s_waitcnt vmcnt(7)
	v_mfma_f32_32x32x16_bf16 v[50:65], v[158:161], v[98:101], v[50:65]
	v_cvt_pk_bf16_f32 v102, v106, v107
	v_cvt_pk_bf16_f32 v103, v108, v109
	v_cvt_pk_bf16_f32 v104, v110, v111
	v_cvt_pk_bf16_f32 v105, v112, v113
	v_mfma_f32_32x32x16_bf16 v[18:33], v[158:161], v[66:69], v[18:33]
	v_cvt_pk_bf16_f32 v70, v74, v75
	v_cvt_pk_bf16_f32 v71, v76, v77
	v_cvt_pk_bf16_f32 v72, v78, v79
	v_cvt_pk_bf16_f32 v73, v80, v81
	s_waitcnt vmcnt(6)
	v_mfma_f32_32x32x16_bf16 v[34:49], v[154:157], v[98:101], v[34:49]
	v_mfma_f32_32x32x16_bf16 v[2:17], v[154:157], v[66:69], v[2:17]
	v_cvt_pk_bf16_f32 v106, v114, v115
	v_cvt_pk_bf16_f32 v107, v116, v117
	v_cvt_pk_bf16_f32 v108, v118, v119
	v_cvt_pk_bf16_f32 v109, v120, v121
	v_cvt_pk_bf16_f32 v74, v82, v83
	v_cvt_pk_bf16_f32 v75, v84, v85
	v_cvt_pk_bf16_f32 v76, v86, v87
	v_cvt_pk_bf16_f32 v77, v88, v89
	s_waitcnt vmcnt(5)
	v_mfma_f32_32x32x16_bf16 v[50:65], v[150:153], v[102:105], v[50:65]
	v_mfma_f32_32x32x16_bf16 v[18:33], v[150:153], v[70:73], v[18:33]
	s_waitcnt vmcnt(4)
	v_mfma_f32_32x32x16_bf16 v[34:49], v[146:149], v[102:105], v[34:49]
	v_mfma_f32_32x32x16_bf16 v[2:17], v[146:149], v[70:73], v[2:17]
	v_cvt_pk_bf16_f32 v110, v122, v123
	v_cvt_pk_bf16_f32 v111, v124, v125
	v_cvt_pk_bf16_f32 v112, v126, v127
	v_cvt_pk_bf16_f32 v113, v128, v129
	v_cvt_pk_bf16_f32 v78, v90, v91
	v_cvt_pk_bf16_f32 v79, v92, v93
	v_cvt_pk_bf16_f32 v80, v94, v95
	v_cvt_pk_bf16_f32 v81, v96, v97
	s_waitcnt vmcnt(3)
	v_mfma_f32_32x32x16_bf16 v[50:65], v[138:141], v[106:109], v[50:65]
	v_mfma_f32_32x32x16_bf16 v[18:33], v[138:141], v[74:77], v[18:33]
	s_waitcnt vmcnt(1)
	v_mfma_f32_32x32x16_bf16 v[34:49], v[142:145], v[106:109], v[34:49]
	v_mfma_f32_32x32x16_bf16 v[2:17], v[142:145], v[74:77], v[2:17]
	v_mfma_f32_32x32x16_bf16 v[50:65], v[134:137], v[110:113], v[50:65]
	v_mfma_f32_32x32x16_bf16 v[18:33], v[134:137], v[78:81], v[18:33]
	s_waitcnt lgkmcnt(0)
	v_add_f32_e32 v210, v210, v211
	v_add_f32_e32 v224, v224, v225
	v_fma_f32 v176, v176, v226, v210
	v_fma_f32 v175, v175, v228, v224
	v_lshl_add_u64 v[168:169], v[168:169], 0, s[84:85]
	v_lshl_add_u64 v[170:171], v[170:171], 0, s[84:85]
	s_waitcnt vmcnt(0)
	v_mfma_f32_32x32x16_bf16 v[34:49], v[130:133], v[110:113], v[34:49]
	v_mfma_f32_32x32x16_bf16 v[2:17], v[130:133], v[78:81], v[2:17]
	v_mov_b32_e32 v177, v188
	v_mov_b32_e32 v189, v218
	v_mov_b32_e32 v199, v236
	s_branch .LBB0_1432
